# full stack + final RMSNorm loop: norm-gain vectors hoisted out of the row loop, per-store reload/vmcnt(0) removed
# baseline (speedup 1.0000x reference)
; __device__ __forceinline__ void unpack8(u32x4 g, f32x4& a, f32x4& b) { a = (f32x4){bf_lo(g.x), bf_hi(g.x), bf_lo(g.y), bf_hi(g.y)}; b = (f32x4){bf_lo(g.z), bf_hi(g.z), bf_lo(g.w), bf_hi(g.w)}; }
; __device__ __forceinline__ void final_phase(const Args& a) {
;     ...
;     const f32x4* fg = (const f32x4*)a.in[I_FNG] + 2 * lane;
;     for (int mrow = gw; mrow < MTOK; mrow += NGW) {
;         const float rs = __builtin_amdgcn_rsqf(ssq[mrow] * (1.0f / DM) + RMS_EPS);
;         const u32x4* hr = (const u32x4*)(HB + (size_t)mrow * DM) + lane; f32x4* orow = (f32x4*)(a.out + (size_t)mrow * DM) + 2 * lane;
;         u32x4 hv[4];
; #pragma unroll
;         for (int j = 0; j < 4; ++j) hv[j] = hr[64 * j];
;         asm volatile("" ::: "memory");
; #pragma unroll
;         for (int j = 0; j < 4; ++j) { f32x4 h0, h1; unpack8(hv[j], h0, h1); orow[128 * j] = h0 * rs * fg[128 * j]; orow[128 * j + 1] = h1 * rs * fg[128 * j + 1]; }
;     }
.LBB0_887:
	s_cmp_lt_i32 s96, 14
	s_cselect_b64 s[0:1], -1, 0
	s_cmp_gt_i32 s97, 13
	s_cselect_b64 s[4:5], -1, 0
	s_and_b64 s[0:1], s[0:1], s[4:5]
	s_and_b64 vcc, exec, s[0:1]
	s_cbranch_vccz .LBB0_891
	s_movk_i32 s0, 0x2000
	v_ashrrev_i32_e32 v0, 6, v188
	v_lshl_add_u32 v0, s2, 3, v0
	v_cmp_gt_i32_e32 vcc, s0, v0
	s_and_saveexec_b64 s[0:1], vcc
	v_readlane_b32 s8, v251, 39
	v_readlane_b32 s9, v251, 40
	v_readlane_b32 s10, v251, 41
	v_readlane_b32 s11, v251, 42
	s_cbranch_execz .LBB0_891
	v_and_b32_e32 v18, 63, v188
	v_readlane_b32 s12, v252, 20
	v_ashrrev_i32_e32 v1, 31, v0
	v_lshlrev_b32_e32 v16, 5, v18
	v_mov_b32_e32 v17, 0
	v_readlane_b32 s26, v252, 34
	v_readlane_b32 s27, v252, 35
	v_lshlrev_b64 v[14:15], 12, v[0:1]
	s_mov_b64 s[2:3], 0x1010
	s_waitcnt lgkmcnt(0)
	v_lshl_add_u64 v[2:3], s[26:27], 0, v[16:17]
	v_lshl_or_b32 v14, v18, 4, v14
	v_lshlrev_b64 v[18:19], 13, v[0:1]
	s_lshl_b32 s0, s58, 3
	v_lshl_add_u64 v[6:7], v[2:3], 0, s[2:3]
	s_mov_b64 s[2:3], 0x1800
	v_or_b32_e32 v18, v18, v16
	s_mov_b64 s[6:7], 0x1000
	v_lshl_add_u64 v[8:9], v[2:3], 0, s[2:3]
	s_mov_b64 s[2:3], 0x1810
	v_mov_b64_e32 v[12:13], 0x10000
	s_ashr_i32 s1, s0, 31
	v_lshl_add_u64 v[16:17], s[8:9], 0, v[18:19]
	v_lshl_add_u64 v[4:5], v[2:3], 0, s[6:7]
	v_lshl_add_u64 v[10:11], v[2:3], 0, s[2:3]
	v_lshl_add_u64 v[12:13], v[0:1], 2, v[12:13]
	s_lshl_b64 s[2:3], s[0:1], 2
	s_lshl_b64 s[4:5], s[0:1], 12
	v_lshl_add_u64 v[16:17], v[16:17], 0, s[6:7]
	s_lshl_b64 s[6:7], s[0:1], 13
	s_mov_b64 s[8:9], 0
	v_mov_b32_e32 v1, 0x358637bd
	s_movk_i32 s1, 0x1fff
	v_readlane_b32 s13, v252, 21
	v_readlane_b32 s14, v252, 22
	v_readlane_b32 s15, v252, 23
	v_readlane_b32 s16, v252, 24
	v_readlane_b32 s17, v252, 25
	v_readlane_b32 s18, v252, 26
	v_readlane_b32 s19, v252, 27
	v_readlane_b32 s20, v252, 28
	v_readlane_b32 s21, v252, 29
	v_readlane_b32 s22, v252, 30
	v_readlane_b32 s23, v252, 31
	v_readlane_b32 s24, v252, 32
	v_readlane_b32 s25, v252, 33
	global_load_dwordx4 v[44:47], v[2:3], off
	global_load_dwordx4 v[48:51], v[2:3], off offset:16
	global_load_dwordx4 v[52:55], v[2:3], off offset:2048
	global_load_dwordx4 v[56:59], v[2:3], off offset:2064
	global_load_dwordx4 v[60:63], v[4:5], off
	global_load_dwordx4 v[64:67], v[6:7], off
	global_load_dwordx4 v[68:71], v[8:9], off
	global_load_dwordx4 v[72:75], v[10:11], off
.LBB0_890:
	v_lshl_add_u64 v[18:19], s[10:11], 0, v[12:13]
	global_load_dword v38, v[18:19], off
	v_lshl_add_u64 v[20:21], s[10:11], 0, v[14:15]
	v_add_co_u32_e32 v34, vcc, 0xfc00000, v20
	v_add_u32_e32 v0, s0, v0
	s_nop 0
	v_addc_co_u32_e32 v35, vcc, 0, v21, vcc
	global_load_dwordx4 v[18:21], v[34:35], off
	global_load_dwordx4 v[22:25], v[34:35], off offset:1024
	global_load_dwordx4 v[26:29], v[34:35], off offset:2048
	global_load_dwordx4 v[30:33], v[34:35], off offset:3072
	v_cmp_lt_i32_e32 vcc, s1, v0
	v_lshl_add_u64 v[12:13], v[12:13], 0, s[2:3]
	v_lshl_add_u64 v[14:15], v[14:15], 0, s[4:5]
	s_or_b64 s[8:9], vcc, s[8:9]
	s_waitcnt vmcnt(0)
	v_fmamk_f32 v38, v38, 0x3a000000, v1
	v_rsq_f32_e32 v38, v38
	v_lshlrev_b32_e32 v40, 16, v18
	v_and_b32_e32 v41, 0xffff0000, v18
	v_lshlrev_b32_e32 v18, 16, v19
	v_and_b32_e32 v19, 0xffff0000, v19
	v_pk_mul_f32 v[40:41], v[38:39], v[40:41] op_sel_hi:[0,1]
	v_pk_mul_f32 v[18:19], v[38:39], v[18:19] op_sel_hi:[0,1]
	v_pk_mul_f32 v[36:37], v[46:47], v[18:19]
	v_pk_mul_f32 v[34:35], v[44:45], v[40:41]
	global_store_dwordx4 v[16:17], v[34:37], off offset:-4096
	v_lshlrev_b32_e32 v18, 16, v20
	v_and_b32_e32 v19, 0xffff0000, v20
	v_lshlrev_b32_e32 v20, 16, v21
	v_and_b32_e32 v21, 0xffff0000, v21
	v_pk_mul_f32 v[20:21], v[38:39], v[20:21] op_sel_hi:[0,1]
	v_pk_mul_f32 v[18:19], v[38:39], v[18:19] op_sel_hi:[0,1]
	v_pk_mul_f32 v[18:19], v[48:49], v[18:19]
	v_pk_mul_f32 v[20:21], v[50:51], v[20:21]
	global_store_dwordx4 v[16:17], v[18:21], off offset:-4080
	v_lshlrev_b32_e32 v34, 16, v22
	v_and_b32_e32 v35, 0xffff0000, v22
	v_lshlrev_b32_e32 v22, 16, v23
	v_and_b32_e32 v23, 0xffff0000, v23
	v_pk_mul_f32 v[22:23], v[38:39], v[22:23] op_sel_hi:[0,1]
	v_pk_mul_f32 v[34:35], v[38:39], v[34:35] op_sel_hi:[0,1]
	v_pk_mul_f32 v[18:19], v[34:35], v[52:53]
	v_pk_mul_f32 v[20:21], v[22:23], v[54:55]
	global_store_dwordx4 v[16:17], v[18:21], off offset:-2048
	v_lshlrev_b32_e32 v22, 16, v24
	v_and_b32_e32 v23, 0xffff0000, v24
	v_lshlrev_b32_e32 v24, 16, v25
	v_and_b32_e32 v25, 0xffff0000, v25
	v_pk_mul_f32 v[24:25], v[38:39], v[24:25] op_sel_hi:[0,1]
	v_pk_mul_f32 v[22:23], v[38:39], v[22:23] op_sel_hi:[0,1]
	v_pk_mul_f32 v[18:19], v[22:23], v[56:57]
	v_pk_mul_f32 v[20:21], v[24:25], v[58:59]
	global_store_dwordx4 v[16:17], v[18:21], off offset:-2032
	v_lshlrev_b32_e32 v22, 16, v26
	v_and_b32_e32 v23, 0xffff0000, v26
	v_lshlrev_b32_e32 v24, 16, v27
	v_and_b32_e32 v25, 0xffff0000, v27
	v_pk_mul_f32 v[24:25], v[38:39], v[24:25] op_sel_hi:[0,1]
	v_pk_mul_f32 v[22:23], v[38:39], v[22:23] op_sel_hi:[0,1]
	v_pk_mul_f32 v[18:19], v[22:23], v[60:61]
	v_pk_mul_f32 v[20:21], v[24:25], v[62:63]
	global_store_dwordx4 v[16:17], v[18:21], off
	v_lshlrev_b32_e32 v22, 16, v28
	v_and_b32_e32 v23, 0xffff0000, v28
	v_lshlrev_b32_e32 v24, 16, v29
	v_and_b32_e32 v25, 0xffff0000, v29
	v_pk_mul_f32 v[24:25], v[38:39], v[24:25] op_sel_hi:[0,1]
	v_pk_mul_f32 v[22:23], v[38:39], v[22:23] op_sel_hi:[0,1]
	v_pk_mul_f32 v[18:19], v[22:23], v[64:65]
	v_pk_mul_f32 v[20:21], v[24:25], v[66:67]
	global_store_dwordx4 v[16:17], v[18:21], off offset:16
	v_lshlrev_b32_e32 v22, 16, v30
	v_and_b32_e32 v23, 0xffff0000, v30
	v_lshlrev_b32_e32 v24, 16, v31
	v_and_b32_e32 v25, 0xffff0000, v31
	v_pk_mul_f32 v[24:25], v[38:39], v[24:25] op_sel_hi:[0,1]
	v_pk_mul_f32 v[22:23], v[38:39], v[22:23] op_sel_hi:[0,1]
	v_pk_mul_f32 v[18:19], v[22:23], v[68:69]
	v_pk_mul_f32 v[20:21], v[24:25], v[70:71]
	global_store_dwordx4 v[16:17], v[18:21], off offset:2048
	v_lshlrev_b32_e32 v22, 16, v32
	v_and_b32_e32 v23, 0xffff0000, v32
	v_lshlrev_b32_e32 v24, 16, v33
	v_and_b32_e32 v25, 0xffff0000, v33
	v_pk_mul_f32 v[24:25], v[38:39], v[24:25] op_sel_hi:[0,1]
	v_pk_mul_f32 v[22:23], v[38:39], v[22:23] op_sel_hi:[0,1]
	v_pk_mul_f32 v[18:19], v[22:23], v[72:73]
	v_pk_mul_f32 v[20:21], v[24:25], v[74:75]
	global_store_dwordx4 v[16:17], v[18:21], off offset:2064
	v_lshl_add_u64 v[16:17], v[16:17], 0, s[6:7]
	s_andn2_b64 exec, exec, s[8:9]
	s_cbranch_execnz .LBB0_890
